# interior steps: cross-lane row-max reduction moved into the (rare) rescale path; the guard tests the per-lane max
# speedup vs baseline: 1.0177x; 1.0014x over previous
; __device__ __forceinline__ float red_max4(float x) {
;     auto a = __builtin_amdgcn_permlane16_swap(__float_as_uint(x), __float_as_uint(x), false, false); x = fmaxf(__uint_as_float(a[0]), __uint_as_float(a[1]));
;     auto b = __builtin_amdgcn_permlane32_swap(__float_as_uint(x), __float_as_uint(x), false, false); return fmaxf(__uint_as_float(b[0]), __uint_as_float(b[1]));
; }
; template <int CGM>
; __device__ __forceinline__ void step_int(const bf16x8 (&kf)[4][2], const bf16x8 (&q)[2][2], float farb, const bool (&selq)[2],
;                                          float (&m)[2], float (&l)[2], f32x4 (&o)[2][4], const unsigned char* Vs, int r, int fq) {
;     f32x4 s[2][4]; float mx[2] = {-1e30f, -1e30f};
; #pragma unroll
;     for (int cg_ = 0; cg_ < 2; ++cg_) if ((CGM >> cg_) & 1) { qk(s[cg_], kf, q[cg_], selq[cg_] ? farb - m[cg_] : -1e30f); mx[cg_] = red_max4(max16v(s[cg_])); }
;     if (__any(mx[0] > 0.f || mx[1] > 0.f)) {
; #pragma unroll
;         for (int cg_ = 0; cg_ < 2; ++cg_) if ((CGM >> cg_) & 1) {
;             const float d = fmaxf(mx[cg_], 0.f), sc = __builtin_amdgcn_exp2f(-d); m[cg_] += d; l[cg_] *= sc;
; #pragma unroll
;             for (int df = 0; df < 4; ++df) o[cg_][df] *= sc;
; #pragma unroll
;             for (int f = 0; f < 4; ++f) s[cg_][f] -= d;
;         }
;     }
.Lsel_c3:
	v_sub_f32_e32 v128, v18, v124
	v_sub_f32_e32 v144, v18, v125
	v_cndmask_b32_e64 v128, v148, v128, s[10:11]
	v_cndmask_b32_e64 v144, v148, v144, s[8:9]
	v_mov_b32_e32 v129, v128
	v_mov_b32_e32 v145, v144
	v_mov_b64_e32 v[130:131], v[128:129]
	v_mov_b64_e32 v[146:147], v[144:145]
	s_waitcnt lgkmcnt(7)
	v_mfma_f32_16x16x32_bf16 v[92:95], v[88:91], v[2:5], v[128:131]
	v_mfma_f32_16x16x32_bf16 v[108:111], v[88:91], v[10:13], v[144:147]
	s_waitcnt lgkmcnt(6)
	v_mfma_f32_16x16x32_bf16 v[96:99], v[80:83], v[2:5], v[128:131]
	v_mfma_f32_16x16x32_bf16 v[112:115], v[80:83], v[10:13], v[144:147]
	s_waitcnt lgkmcnt(5)
	v_mfma_f32_16x16x32_bf16 v[92:95], v[84:87], v[6:9], v[92:95]
	v_mfma_f32_16x16x32_bf16 v[108:111], v[84:87], v[14:17], v[108:111]
	s_waitcnt lgkmcnt(4)
	v_mfma_f32_16x16x32_bf16 v[96:99], v[76:79], v[6:9], v[96:99]
	v_mfma_f32_16x16x32_bf16 v[112:115], v[76:79], v[14:17], v[112:115]
	s_waitcnt lgkmcnt(3)
	v_mfma_f32_16x16x32_bf16 v[100:103], v[72:75], v[2:5], v[128:131]
	v_mfma_f32_16x16x32_bf16 v[116:119], v[72:75], v[10:13], v[144:147]
	s_waitcnt lgkmcnt(2)
	v_mfma_f32_16x16x32_bf16 v[104:107], v[60:63], v[2:5], v[128:131]
	v_mfma_f32_16x16x32_bf16 v[120:123], v[60:63], v[10:13], v[144:147]
	s_waitcnt lgkmcnt(1)
	v_mfma_f32_16x16x32_bf16 v[100:103], v[68:71], v[6:9], v[100:103]
	v_mfma_f32_16x16x32_bf16 v[116:119], v[68:71], v[14:17], v[116:119]
	s_waitcnt lgkmcnt(0)
	v_mfma_f32_16x16x32_bf16 v[104:107], v[64:67], v[6:9], v[104:107]
	v_mfma_f32_16x16x32_bf16 v[120:123], v[64:67], v[14:17], v[120:123]
	ds_read_b128 v[88:91], v143 offset:8192
	ds_read_b128 v[80:83], v143 offset:8704
	ds_read_b128 v[72:75], v143 offset:12288
	ds_read_b128 v[60:63], v143 offset:12800
	v_max3_f32 v128, v92, v93, v94
	v_max3_f32 v129, v95, v96, v97
	v_max3_f32 v144, v108, v109, v110
	v_max3_f32 v145, v111, v112, v113
	v_max3_f32 v130, v98, v99, v100
	v_max3_f32 v131, v101, v102, v103
	v_max3_f32 v146, v114, v115, v116
	v_max3_f32 v147, v117, v118, v119
	v_max3_f32 v128, v128, v104, v105
	v_max3_f32 v129, v129, v106, v107
	v_max3_f32 v144, v144, v120, v121
	v_max3_f32 v145, v145, v122, v123
	v_max3_f32 v128, v128, v129, v130
	v_max3_f32 v144, v144, v145, v146
	v_max_f32_e32 v128, v128, v131
	v_max_f32_e32 v144, v144, v147
	ds_read_b128 v[84:87], v142 offset:8192
	ds_read_b128 v[76:79], v142 offset:8704
	v_max_f32_e32 v129, v128, v144
	ds_read_b128 v[68:71], v142 offset:12288
	ds_read_b128 v[64:67], v142 offset:12800
	v_cmp_lt_f32_e32 vcc, 4.0, v129
	s_cbranch_vccz .Lsel_c3_exp
	v_mov_b32_e32 v129, v128
	v_mov_b32_e32 v145, v144
	s_nop 1
	v_permlane16_swap_b32_e32 v128, v129
	v_permlane16_swap_b32_e32 v144, v145
	v_max_f32_e32 v128, v128, v129
	v_max_f32_e32 v144, v144, v145
	v_mov_b32_e32 v129, v128
	v_mov_b32_e32 v145, v144
	s_nop 1
	v_permlane32_swap_b32_e32 v128, v129
	v_permlane32_swap_b32_e32 v144, v145
	v_max_f32_e32 v128, v128, v129
	v_max_f32_e32 v144, v144, v145
	v_max_f32_e32 v130, 0, v128
	v_max_f32_e32 v147, 0, v144
	v_exp_f32_e64 v128, -v130
	v_exp_f32_e64 v146, -v147
	v_add_f32_e32 v124, v124, v130
	v_add_f32_e32 v125, v125, v147
	v_sub_f32_e32 v92, v92, v130
	v_sub_f32_e32 v93, v93, v130
	v_sub_f32_e32 v94, v94, v130
	v_sub_f32_e32 v95, v95, v130
	v_sub_f32_e32 v96, v96, v130
	v_sub_f32_e32 v97, v97, v130
	v_sub_f32_e32 v98, v98, v130
	v_sub_f32_e32 v99, v99, v130
	v_sub_f32_e32 v100, v100, v130
	v_sub_f32_e32 v101, v101, v130
	v_sub_f32_e32 v102, v102, v130
	v_sub_f32_e32 v103, v103, v130
	v_sub_f32_e32 v104, v104, v130
	v_sub_f32_e32 v105, v105, v130
	v_sub_f32_e32 v106, v106, v130
	v_sub_f32_e32 v107, v107, v130
	v_sub_f32_e32 v108, v108, v147
	v_sub_f32_e32 v109, v109, v147
	v_sub_f32_e32 v110, v110, v147
	v_sub_f32_e32 v111, v111, v147
	v_sub_f32_e32 v112, v112, v147
	v_sub_f32_e32 v113, v113, v147
	v_sub_f32_e32 v114, v114, v147
	v_sub_f32_e32 v115, v115, v147
	v_sub_f32_e32 v116, v116, v147
	v_sub_f32_e32 v117, v117, v147
	v_sub_f32_e32 v118, v118, v147
	v_sub_f32_e32 v119, v119, v147
	v_sub_f32_e32 v120, v120, v147
	v_sub_f32_e32 v121, v121, v147
	v_sub_f32_e32 v122, v122, v147
	v_sub_f32_e32 v123, v123, v147
	v_mul_f32_e32 v127, v127, v128
	v_pk_mul_f32 v[56:57], v[56:57], v[128:129] op_sel_hi:[1,0]
	v_pk_mul_f32 v[58:59], v[58:59], v[128:129] op_sel_hi:[1,0]
	v_pk_mul_f32 v[52:53], v[52:53], v[128:129] op_sel_hi:[1,0]
	v_pk_mul_f32 v[54:55], v[54:55], v[128:129] op_sel_hi:[1,0]
	v_pk_mul_f32 v[48:49], v[48:49], v[128:129] op_sel_hi:[1,0]
	v_pk_mul_f32 v[50:51], v[50:51], v[128:129] op_sel_hi:[1,0]
	v_pk_mul_f32 v[44:45], v[44:45], v[128:129] op_sel_hi:[1,0]
	v_pk_mul_f32 v[46:47], v[46:47], v[128:129] op_sel_hi:[1,0]
	v_mul_f32_e32 v126, v126, v146
	v_pk_mul_f32 v[40:41], v[40:41], v[146:147] op_sel_hi:[1,0]
	v_pk_mul_f32 v[42:43], v[42:43], v[146:147] op_sel_hi:[1,0]
	v_pk_mul_f32 v[28:29], v[28:29], v[146:147] op_sel_hi:[1,0]
	v_pk_mul_f32 v[30:31], v[30:31], v[146:147] op_sel_hi:[1,0]
	v_pk_mul_f32 v[24:25], v[24:25], v[146:147] op_sel_hi:[1,0]
	v_pk_mul_f32 v[26:27], v[26:27], v[146:147] op_sel_hi:[1,0]
	v_pk_mul_f32 v[20:21], v[20:21], v[146:147] op_sel_hi:[1,0]
	v_pk_mul_f32 v[22:23], v[22:23], v[146:147] op_sel_hi:[1,0]

; __device__ __forceinline__ float red_max4(float x) {
;     auto a = __builtin_amdgcn_permlane16_swap(__float_as_uint(x), __float_as_uint(x), false, false); x = fmaxf(__uint_as_float(a[0]), __uint_as_float(a[1]));
;     auto b = __builtin_amdgcn_permlane32_swap(__float_as_uint(x), __float_as_uint(x), false, false); return fmaxf(__uint_as_float(b[0]), __uint_as_float(b[1]));
; }
; template <int CGM>
; __device__ __forceinline__ void step_int(const bf16x8 (&kf)[4][2], const bf16x8 (&q)[2][2], float farb, const bool (&selq)[2],
;                                          float (&m)[2], float (&l)[2], f32x4 (&o)[2][4], const unsigned char* Vs, int r, int fq) {
;     f32x4 s[2][4]; float mx[2] = {-1e30f, -1e30f};
; #pragma unroll
;     for (int cg_ = 0; cg_ < 2; ++cg_) if ((CGM >> cg_) & 1) { qk(s[cg_], kf, q[cg_], selq[cg_] ? farb - m[cg_] : -1e30f); mx[cg_] = red_max4(max16v(s[cg_])); }
;     if (__any(mx[0] > 0.f || mx[1] > 0.f)) {
; #pragma unroll
;         for (int cg_ = 0; cg_ < 2; ++cg_) if ((CGM >> cg_) & 1) {
;             const float d = fmaxf(mx[cg_], 0.f), sc = __builtin_amdgcn_exp2f(-d); m[cg_] += d; l[cg_] *= sc;
; #pragma unroll
;             for (int df = 0; df < 4; ++df) o[cg_][df] *= sc;
; #pragma unroll
;             for (int f = 0; f < 4; ++f) s[cg_][f] -= d;
;         }
;     }
.Lsel_c1:
	v_sub_f32_e32 v128, v18, v124
	v_cndmask_b32_e64 v128, v148, v128, s[10:11]
	v_mov_b32_e32 v129, v128
	v_mov_b64_e32 v[130:131], v[128:129]
	s_nop 0
	s_waitcnt lgkmcnt(7)
	v_mfma_f32_16x16x32_bf16 v[92:95], v[88:91], v[2:5], v[128:131]
	s_waitcnt lgkmcnt(6)
	v_mfma_f32_16x16x32_bf16 v[96:99], v[80:83], v[2:5], v[128:131]
	s_waitcnt lgkmcnt(5)
	v_mfma_f32_16x16x32_bf16 v[92:95], v[84:87], v[6:9], v[92:95]
	s_waitcnt lgkmcnt(4)
	v_mfma_f32_16x16x32_bf16 v[96:99], v[76:79], v[6:9], v[96:99]
	s_waitcnt lgkmcnt(3)
	v_mfma_f32_16x16x32_bf16 v[100:103], v[72:75], v[2:5], v[128:131]
	s_waitcnt lgkmcnt(2)
	v_mfma_f32_16x16x32_bf16 v[104:107], v[60:63], v[2:5], v[128:131]
	s_waitcnt lgkmcnt(1)
	v_mfma_f32_16x16x32_bf16 v[100:103], v[68:71], v[6:9], v[100:103]
	s_waitcnt lgkmcnt(0)
	v_mfma_f32_16x16x32_bf16 v[104:107], v[64:67], v[6:9], v[104:107]
	ds_read_b128 v[88:91], v143 offset:8192
	ds_read_b128 v[80:83], v143 offset:8704
	ds_read_b128 v[72:75], v143 offset:12288
	ds_read_b128 v[60:63], v143 offset:12800
	v_max3_f32 v128, v92, v93, v94
	v_max3_f32 v129, v95, v96, v97
	v_max3_f32 v130, v98, v99, v100
	v_max3_f32 v131, v101, v102, v103
	v_max3_f32 v128, v128, v104, v105
	v_max3_f32 v129, v129, v106, v107
	v_max3_f32 v128, v128, v129, v130
	v_max_f32_e32 v128, v128, v131
	ds_read_b128 v[84:87], v142 offset:8192
	ds_read_b128 v[76:79], v142 offset:8704
	ds_read_b128 v[68:71], v142 offset:12288
	ds_read_b128 v[64:67], v142 offset:12800
	v_cmp_lt_f32_e32 vcc, 4.0, v128
	s_cbranch_vccz .Lsel_c1_exp
	v_mov_b32_e32 v129, v128
	s_nop 1
	v_permlane16_swap_b32_e32 v128, v129
	s_nop 1
	v_max_f32_e32 v128, v128, v129
	v_mov_b32_e32 v129, v128
	s_nop 1
	v_permlane32_swap_b32_e32 v128, v129
	s_nop 1
	v_max_f32_e32 v128, v128, v129
	v_max_f32_e32 v130, 0, v128
	v_exp_f32_e64 v128, -v130
	v_add_f32_e32 v124, v124, v130
	v_sub_f32_e32 v92, v92, v130
	v_sub_f32_e32 v93, v93, v130
	v_sub_f32_e32 v94, v94, v130
	v_sub_f32_e32 v95, v95, v130
	v_sub_f32_e32 v96, v96, v130
	v_sub_f32_e32 v97, v97, v130
	v_sub_f32_e32 v98, v98, v130
	v_sub_f32_e32 v99, v99, v130
	v_sub_f32_e32 v100, v100, v130
	v_sub_f32_e32 v101, v101, v130
	v_sub_f32_e32 v102, v102, v130
	v_sub_f32_e32 v103, v103, v130
	v_sub_f32_e32 v104, v104, v130
	v_sub_f32_e32 v105, v105, v130
	v_sub_f32_e32 v106, v106, v130
	v_sub_f32_e32 v107, v107, v130
	v_mul_f32_e32 v127, v127, v128
	v_pk_mul_f32 v[56:57], v[56:57], v[128:129] op_sel_hi:[1,0]
	v_pk_mul_f32 v[58:59], v[58:59], v[128:129] op_sel_hi:[1,0]
	v_pk_mul_f32 v[52:53], v[52:53], v[128:129] op_sel_hi:[1,0]
	v_pk_mul_f32 v[54:55], v[54:55], v[128:129] op_sel_hi:[1,0]
	v_pk_mul_f32 v[48:49], v[48:49], v[128:129] op_sel_hi:[1,0]
	v_pk_mul_f32 v[50:51], v[50:51], v[128:129] op_sel_hi:[1,0]
	v_pk_mul_f32 v[44:45], v[44:45], v[128:129] op_sel_hi:[1,0]
	v_pk_mul_f32 v[46:47], v[46:47], v[128:129] op_sel_hi:[1,0]

; __device__ __forceinline__ float red_max4(float x) {
;     auto a = __builtin_amdgcn_permlane16_swap(__float_as_uint(x), __float_as_uint(x), false, false); x = fmaxf(__uint_as_float(a[0]), __uint_as_float(a[1]));
;     auto b = __builtin_amdgcn_permlane32_swap(__float_as_uint(x), __float_as_uint(x), false, false); return fmaxf(__uint_as_float(b[0]), __uint_as_float(b[1]));
; }
; template <int CGM>
; __device__ __forceinline__ void step_int(const bf16x8 (&kf)[4][2], const bf16x8 (&q)[2][2], float farb, const bool (&selq)[2],
;                                          float (&m)[2], float (&l)[2], f32x4 (&o)[2][4], const unsigned char* Vs, int r, int fq) {
;     f32x4 s[2][4]; float mx[2] = {-1e30f, -1e30f};
; #pragma unroll
;     for (int cg_ = 0; cg_ < 2; ++cg_) if ((CGM >> cg_) & 1) { qk(s[cg_], kf, q[cg_], selq[cg_] ? farb - m[cg_] : -1e30f); mx[cg_] = red_max4(max16v(s[cg_])); }
;     if (__any(mx[0] > 0.f || mx[1] > 0.f)) {
; #pragma unroll
;         for (int cg_ = 0; cg_ < 2; ++cg_) if ((CGM >> cg_) & 1) {
;             const float d = fmaxf(mx[cg_], 0.f), sc = __builtin_amdgcn_exp2f(-d); m[cg_] += d; l[cg_] *= sc;
; #pragma unroll
;             for (int df = 0; df < 4; ++df) o[cg_][df] *= sc;
; #pragma unroll
;             for (int f = 0; f < 4; ++f) s[cg_][f] -= d;
;         }
;     }
.Lsel_c2:
	v_sub_f32_e32 v144, v18, v125
	v_cndmask_b32_e64 v144, v148, v144, s[8:9]
	v_mov_b32_e32 v145, v144
	v_mov_b64_e32 v[146:147], v[144:145]
	s_nop 0
	s_waitcnt lgkmcnt(7)
	v_mfma_f32_16x16x32_bf16 v[108:111], v[88:91], v[10:13], v[144:147]
	s_waitcnt lgkmcnt(6)
	v_mfma_f32_16x16x32_bf16 v[112:115], v[80:83], v[10:13], v[144:147]
	s_waitcnt lgkmcnt(5)
	v_mfma_f32_16x16x32_bf16 v[108:111], v[84:87], v[14:17], v[108:111]
	s_waitcnt lgkmcnt(4)
	v_mfma_f32_16x16x32_bf16 v[112:115], v[76:79], v[14:17], v[112:115]
	s_waitcnt lgkmcnt(3)
	v_mfma_f32_16x16x32_bf16 v[116:119], v[72:75], v[10:13], v[144:147]
	s_waitcnt lgkmcnt(2)
	v_mfma_f32_16x16x32_bf16 v[120:123], v[60:63], v[10:13], v[144:147]
	s_waitcnt lgkmcnt(1)
	v_mfma_f32_16x16x32_bf16 v[116:119], v[68:71], v[14:17], v[116:119]
	s_waitcnt lgkmcnt(0)
	v_mfma_f32_16x16x32_bf16 v[120:123], v[64:67], v[14:17], v[120:123]
	ds_read_b128 v[88:91], v143 offset:8192
	ds_read_b128 v[80:83], v143 offset:8704
	ds_read_b128 v[72:75], v143 offset:12288
	ds_read_b128 v[60:63], v143 offset:12800
	v_max3_f32 v144, v108, v109, v110
	v_max3_f32 v145, v111, v112, v113
	v_max3_f32 v146, v114, v115, v116
	v_max3_f32 v147, v117, v118, v119
	v_max3_f32 v144, v144, v120, v121
	v_max3_f32 v145, v145, v122, v123
	v_max3_f32 v144, v144, v145, v146
	v_max_f32_e32 v144, v144, v147
	ds_read_b128 v[84:87], v142 offset:8192
	ds_read_b128 v[76:79], v142 offset:8704
	ds_read_b128 v[68:71], v142 offset:12288
	ds_read_b128 v[64:67], v142 offset:12800
	v_cmp_lt_f32_e32 vcc, 4.0, v144
	s_cbranch_vccz .Lsel_c2_exp
	v_mov_b32_e32 v145, v144
	s_nop 1
	v_permlane16_swap_b32_e32 v144, v145
	s_nop 1
	v_max_f32_e32 v144, v144, v145
	v_mov_b32_e32 v145, v144
	s_nop 1
	v_permlane32_swap_b32_e32 v144, v145
	s_nop 1
	v_max_f32_e32 v144, v144, v145
	v_max_f32_e32 v147, 0, v144
	v_exp_f32_e64 v146, -v147
	v_add_f32_e32 v125, v125, v147
	v_sub_f32_e32 v108, v108, v147
	v_sub_f32_e32 v109, v109, v147
	v_sub_f32_e32 v110, v110, v147
	v_sub_f32_e32 v111, v111, v147
	v_sub_f32_e32 v112, v112, v147
	v_sub_f32_e32 v113, v113, v147
	v_sub_f32_e32 v114, v114, v147
	v_sub_f32_e32 v115, v115, v147
	v_sub_f32_e32 v116, v116, v147
	v_sub_f32_e32 v117, v117, v147
	v_sub_f32_e32 v118, v118, v147
	v_sub_f32_e32 v119, v119, v147
	v_sub_f32_e32 v120, v120, v147
	v_sub_f32_e32 v121, v121, v147
	v_sub_f32_e32 v122, v122, v147
	v_sub_f32_e32 v123, v123, v147
	v_mul_f32_e32 v126, v126, v146
	v_pk_mul_f32 v[40:41], v[40:41], v[146:147] op_sel_hi:[1,0]
	v_pk_mul_f32 v[42:43], v[42:43], v[146:147] op_sel_hi:[1,0]
	v_pk_mul_f32 v[28:29], v[28:29], v[146:147] op_sel_hi:[1,0]
	v_pk_mul_f32 v[30:31], v[30:31], v[146:147] op_sel_hi:[1,0]
	v_pk_mul_f32 v[24:25], v[24:25], v[146:147] op_sel_hi:[1,0]
	v_pk_mul_f32 v[26:27], v[26:27], v[146:147] op_sel_hi:[1,0]
	v_pk_mul_f32 v[20:21], v[20:21], v[146:147] op_sel_hi:[1,0]
	v_pk_mul_f32 v[22:23], v[22:23], v[146:147] op_sel_hi:[1,0]

; __device__ __forceinline__ float red_max4(float x) {
;     auto a = __builtin_amdgcn_permlane16_swap(__float_as_uint(x), __float_as_uint(x), false, false); x = fmaxf(__uint_as_float(a[0]), __uint_as_float(a[1]));
;     auto b = __builtin_amdgcn_permlane32_swap(__float_as_uint(x), __float_as_uint(x), false, false); return fmaxf(__uint_as_float(b[0]), __uint_as_float(b[1]));
; }
; template <int CGM>
; __device__ __forceinline__ void step_int(const bf16x8 (&kf)[4][2], const bf16x8 (&q)[2][2], float farb, const bool (&selq)[2],
;                                          float (&m)[2], float (&l)[2], f32x4 (&o)[2][4], const unsigned char* Vs, int r, int fq) {
;     f32x4 s[2][4]; float mx[2] = {-1e30f, -1e30f};
; #pragma unroll
;     for (int cg_ = 0; cg_ < 2; ++cg_) if ((CGM >> cg_) & 1) { qk(s[cg_], kf, q[cg_], selq[cg_] ? farb - m[cg_] : -1e30f); mx[cg_] = red_max4(max16v(s[cg_])); }
;     if (__any(mx[0] > 0.f || mx[1] > 0.f)) {
; #pragma unroll
;         for (int cg_ = 0; cg_ < 2; ++cg_) if ((CGM >> cg_) & 1) {
;             const float d = fmaxf(mx[cg_], 0.f), sc = __builtin_amdgcn_exp2f(-d); m[cg_] += d; l[cg_] *= sc;
; #pragma unroll
;             for (int df = 0; df < 4; ++df) o[cg_][df] *= sc;
; #pragma unroll
;             for (int f = 0; f < 4; ++f) s[cg_][f] -= d;
;         }
;     }
.Lwin_int:
	v_sub_f32_e32 v188, v18, v156
	v_sub_f32_e32 v192, v18, v157
	v_mov_b32_e32 v189, v188
	v_mov_b32_e32 v193, v192
	v_mov_b64_e32 v[190:191], v[188:189]
	v_mov_b64_e32 v[194:195], v[192:193]
	s_waitcnt lgkmcnt(7)
	v_mfma_f32_16x16x32_bf16 v[116:119], v[80:83], v[2:5], v[188:191]
	v_mfma_f32_16x16x32_bf16 v[136:139], v[80:83], v[10:13], v[192:195]
	s_waitcnt lgkmcnt(6)
	v_mfma_f32_16x16x32_bf16 v[120:123], v[72:75], v[2:5], v[188:191]
	v_mfma_f32_16x16x32_bf16 v[140:143], v[72:75], v[10:13], v[192:195]
	s_waitcnt lgkmcnt(5)
	v_mfma_f32_16x16x32_bf16 v[116:119], v[76:79], v[6:9], v[116:119]
	v_mfma_f32_16x16x32_bf16 v[136:139], v[76:79], v[14:17], v[136:139]
	s_waitcnt lgkmcnt(4)
	v_mfma_f32_16x16x32_bf16 v[120:123], v[68:71], v[6:9], v[120:123]
	v_mfma_f32_16x16x32_bf16 v[140:143], v[68:71], v[14:17], v[140:143]
	s_waitcnt lgkmcnt(3)
	v_mfma_f32_16x16x32_bf16 v[124:127], v[60:63], v[2:5], v[188:191]
	v_mfma_f32_16x16x32_bf16 v[144:147], v[60:63], v[10:13], v[192:195]
	s_waitcnt lgkmcnt(2)
	v_mfma_f32_16x16x32_bf16 v[132:135], v[56:59], v[2:5], v[188:191]
	v_mfma_f32_16x16x32_bf16 v[184:187], v[56:59], v[10:13], v[192:195]
	s_waitcnt lgkmcnt(1)
	v_mfma_f32_16x16x32_bf16 v[124:127], v[64:67], v[6:9], v[124:127]
	v_mfma_f32_16x16x32_bf16 v[144:147], v[64:67], v[14:17], v[144:147]
	s_waitcnt lgkmcnt(0)
	v_mfma_f32_16x16x32_bf16 v[132:135], v[52:55], v[6:9], v[132:135]
	v_mfma_f32_16x16x32_bf16 v[184:187], v[52:55], v[14:17], v[184:187]
	ds_read_b128 v[80:83], v149 offset:8192
	ds_read_b128 v[72:75], v149 offset:8704
	ds_read_b128 v[60:63], v149 offset:12288
	ds_read_b128 v[56:59], v149 offset:12800
	v_max3_f32 v188, v116, v117, v118
	v_max3_f32 v189, v119, v120, v121
	v_max3_f32 v192, v136, v137, v138
	v_max3_f32 v193, v139, v140, v141
	v_max3_f32 v190, v122, v123, v124
	v_max3_f32 v191, v125, v126, v127
	v_max3_f32 v194, v142, v143, v144
	v_max3_f32 v195, v145, v146, v147
	v_max3_f32 v188, v188, v132, v133
	v_max3_f32 v189, v189, v134, v135
	v_max3_f32 v192, v192, v184, v185
	v_max3_f32 v193, v193, v186, v187
	v_max3_f32 v188, v188, v189, v190
	v_max3_f32 v192, v192, v193, v194
	v_max_f32_e32 v188, v188, v191
	v_max_f32_e32 v192, v192, v195
	ds_read_b128 v[76:79], v182 offset:8192
	ds_read_b128 v[68:71], v182 offset:8704
	v_max_f32_e32 v189, v188, v192
	ds_read_b128 v[64:67], v182 offset:12288
	ds_read_b128 v[52:55], v182 offset:12800
	v_cmp_lt_f32_e32 vcc, 4.0, v189
	s_cbranch_vccz .Lwin_int_exp
	v_mov_b32_e32 v189, v188
	v_mov_b32_e32 v193, v192
	s_nop 1
	v_permlane16_swap_b32_e32 v188, v189
	v_permlane16_swap_b32_e32 v192, v193
	v_max_f32_e32 v188, v188, v189
	v_max_f32_e32 v192, v192, v193
	v_mov_b32_e32 v189, v188
	v_mov_b32_e32 v193, v192
	s_nop 1
	v_permlane32_swap_b32_e32 v188, v189
	v_permlane32_swap_b32_e32 v192, v193
	v_max_f32_e32 v188, v188, v189
	v_max_f32_e32 v192, v192, v193
	v_max_f32_e32 v190, 0, v188
	v_max_f32_e32 v195, 0, v192
	v_exp_f32_e64 v188, -v190
	v_exp_f32_e64 v194, -v195
	v_add_f32_e32 v156, v156, v190
	v_add_f32_e32 v157, v157, v195
	v_sub_f32_e32 v116, v116, v190
	v_sub_f32_e32 v117, v117, v190
	v_sub_f32_e32 v118, v118, v190
	v_sub_f32_e32 v119, v119, v190
	v_sub_f32_e32 v120, v120, v190
	v_sub_f32_e32 v121, v121, v190
	v_sub_f32_e32 v122, v122, v190
	v_sub_f32_e32 v123, v123, v190
	v_sub_f32_e32 v124, v124, v190
	v_sub_f32_e32 v125, v125, v190
	v_sub_f32_e32 v126, v126, v190
	v_sub_f32_e32 v127, v127, v190
	v_sub_f32_e32 v132, v132, v190
	v_sub_f32_e32 v133, v133, v190
	v_sub_f32_e32 v134, v134, v190
	v_sub_f32_e32 v135, v135, v190
	v_sub_f32_e32 v136, v136, v195
	v_sub_f32_e32 v137, v137, v195
	v_sub_f32_e32 v138, v138, v195
	v_sub_f32_e32 v139, v139, v195
	v_sub_f32_e32 v140, v140, v195
	v_sub_f32_e32 v141, v141, v195
	v_sub_f32_e32 v142, v142, v195
	v_sub_f32_e32 v143, v143, v195
	v_sub_f32_e32 v144, v144, v195
	v_sub_f32_e32 v145, v145, v195
	v_sub_f32_e32 v146, v146, v195
	v_sub_f32_e32 v147, v147, v195
	v_sub_f32_e32 v184, v184, v195
	v_sub_f32_e32 v185, v185, v195
	v_sub_f32_e32 v186, v186, v195
	v_sub_f32_e32 v187, v187, v195
	v_mul_f32_e32 v155, v155, v188
	v_pk_mul_f32 v[48:49], v[48:49], v[188:189] op_sel_hi:[1,0]
	v_pk_mul_f32 v[50:51], v[50:51], v[188:189] op_sel_hi:[1,0]
	v_pk_mul_f32 v[40:41], v[40:41], v[188:189] op_sel_hi:[1,0]
	v_pk_mul_f32 v[42:43], v[42:43], v[188:189] op_sel_hi:[1,0]
	v_pk_mul_f32 v[32:33], v[32:33], v[188:189] op_sel_hi:[1,0]
	v_pk_mul_f32 v[34:35], v[34:35], v[188:189] op_sel_hi:[1,0]
	v_pk_mul_f32 v[24:25], v[24:25], v[188:189] op_sel_hi:[1,0]
	v_pk_mul_f32 v[26:27], v[26:27], v[188:189] op_sel_hi:[1,0]
	v_mul_f32_e32 v154, v154, v194
	v_pk_mul_f32 v[44:45], v[44:45], v[194:195] op_sel_hi:[1,0]
	v_pk_mul_f32 v[46:47], v[46:47], v[194:195] op_sel_hi:[1,0]
	v_pk_mul_f32 v[36:37], v[36:37], v[194:195] op_sel_hi:[1,0]
	v_pk_mul_f32 v[38:39], v[38:39], v[194:195] op_sel_hi:[1,0]
	v_pk_mul_f32 v[28:29], v[28:29], v[194:195] op_sel_hi:[1,0]
	v_pk_mul_f32 v[30:31], v[30:31], v[194:195] op_sel_hi:[1,0]
	v_pk_mul_f32 v[20:21], v[20:21], v[194:195] op_sel_hi:[1,0]
	v_pk_mul_f32 v[22:23], v[22:23], v[194:195] op_sel_hi:[1,0]
